# PW phase: the four LoRA second-stage MFMA blocks (decay, value, gate, akr) now issue all W2T fragment loads up front as global_load with counted vmcnt waits; gate block unrolled 5x with double-buffere
# speedup vs baseline: 1.0308x; 1.0018x over previous
.LBB0_617:
	s_or_b64 exec, exec, s[40:41]
	v_mov_b64_e32 v[92:93], v[118:119]
	s_waitcnt lgkmcnt(0)
	s_barrier
	ds_read_b128 v[50:53], v150
	ds_read_b128 v[68:71], v150 offset:32
	ds_read_b128 v[76:79], v150 offset:64
	ds_read_b128 v[72:75], v150 offset:96
	v_add_co_u32_e32 v134, vcc, 0x5000, v92
	s_nop 1
	v_addc_co_u32_e32 v135, vcc, 0, v93, vcc
	s_mov_b32 s0, 0xa000
	v_add_co_u32_e32 v136, vcc, s0, v92
	s_nop 1
	v_addc_co_u32_e32 v137, vcc, 0, v93, vcc
	v_add_co_u32_e32 v138, vcc, 0xf000, v92
	s_nop 1
	v_addc_co_u32_e32 v139, vcc, 0, v93, vcc
	global_load_dwordx4 v[184:187], v[92:93], off
	global_load_dwordx4 v[188:191], v[92:93], off offset:32
	global_load_dwordx4 v[200:203], v[134:135], off
	global_load_dwordx4 v[218:221], v[134:135], off offset:32
	global_load_dwordx4 v[230:233], v[136:137], off
	global_load_dwordx4 v[234:237], v[136:137], off offset:32
	global_load_dwordx4 v[192:195], v[92:93], off offset:64
	global_load_dwordx4 v[222:225], v[134:135], off offset:64
	global_load_dwordx4 v[238:241], v[136:137], off offset:64
	global_load_dwordx4 v[196:199], v[92:93], off offset:96
	global_load_dwordx4 v[226:229], v[134:135], off offset:96
	global_load_dwordx4 v[130:133], v[136:137], off offset:96
	global_load_dwordx4 v[54:57], v[138:139], off
	global_load_dwordx4 v[88:91], v[138:139], off offset:32
	global_load_dwordx4 v[84:87], v[138:139], off offset:64
	global_load_dwordx4 v[80:83], v[138:139], off offset:96
	global_load_dwordx4 v[58:61], v[110:111], off
	v_cndmask_b32_e64 v128, v151, v153, s[42:43]
	v_mov_b32_e32 v66, v128
	s_and_b32 s46, s57, 0x7e0
	s_and_b64 s[0:1], s[42:43], exec
	s_cselect_b32 s58, 2, 1
	s_lshl_b32 s0, s56, 9
	s_and_b32 s25, s0, 0xffff8000
	s_add_i32 s60, s54, s25
	s_movk_i32 s28, 0x2000
	v_mov_b32_e32 v96, v157
	s_add_i32 s60, s60, s46
	s_mov_b32 s44, s58
	v_lshl_add_u64 v[94:95], v[66:67], 2, s[92:93]
	s_waitcnt vmcnt(16) lgkmcnt(3)
	v_mfma_f32_32x32x16_bf16 v[18:33], v[184:187], v[50:53], 0
	s_waitcnt vmcnt(15) lgkmcnt(2)
	v_mfma_f32_32x32x16_bf16 v[18:33], v[188:191], v[68:71], v[18:33]
	s_waitcnt vmcnt(14) lgkmcnt(3)
	v_mfma_f32_32x32x16_bf16 v[34:49], v[200:203], v[50:53], 0
	s_waitcnt vmcnt(13) lgkmcnt(2)
	v_mfma_f32_32x32x16_bf16 v[34:49], v[218:221], v[68:71], v[34:49]
	s_waitcnt vmcnt(12) lgkmcnt(3)
	v_mfma_f32_32x32x16_bf16 v[2:17], v[230:233], v[50:53], 0
	s_waitcnt vmcnt(11) lgkmcnt(2)
	v_mfma_f32_32x32x16_bf16 v[2:17], v[234:237], v[68:71], v[2:17]
	s_waitcnt vmcnt(10) lgkmcnt(1)
	v_mfma_f32_32x32x16_bf16 v[18:33], v[192:195], v[76:79], v[18:33]
	s_waitcnt vmcnt(9) lgkmcnt(1)
	v_mfma_f32_32x32x16_bf16 v[34:49], v[222:225], v[76:79], v[34:49]
	s_waitcnt vmcnt(8) lgkmcnt(1)
	v_mfma_f32_32x32x16_bf16 v[2:17], v[238:241], v[76:79], v[2:17]
	s_waitcnt vmcnt(7) lgkmcnt(0)
	v_mfma_f32_32x32x16_bf16 v[18:33], v[196:199], v[72:75], v[18:33]
	s_waitcnt vmcnt(6) lgkmcnt(0)
	v_mfma_f32_32x32x16_bf16 v[34:49], v[226:229], v[72:75], v[34:49]
	s_nop 10
	ds_write_b128 v159, v[18:21] offset:21504
	ds_write_b128 v159, v[22:25] offset:21536
	ds_write_b128 v159, v[26:29] offset:21568
	ds_write_b128 v159, v[30:33] offset:21600
	ds_write_b128 v159, v[34:37] offset:21632
	ds_write_b128 v159, v[38:41] offset:21664
	ds_write_b128 v159, v[42:45] offset:21696
	ds_write_b128 v159, v[46:49] offset:21728
	s_waitcnt vmcnt(5)
	v_mfma_f32_32x32x16_bf16 v[2:17], v[130:133], v[72:75], v[2:17]
	s_waitcnt vmcnt(0)
	s_branch .LBB0_619

.LBB0_653:
	s_and_b64 vcc, exec, s[6:7]
	s_cbranch_vccz .LBB0_655
	ds_read_b128 v[130:133], v150 offset:576
	ds_read_b128 v[134:137], v150 offset:608
	v_add_co_u32_e32 v138, vcc, 0x5000, v92
	s_nop 1
	v_addc_co_u32_e32 v139, vcc, 0, v93, vcc
	v_add_co_u32_e32 v140, vcc, 0xa000, v92
	s_nop 1
	v_addc_co_u32_e32 v141, vcc, 0, v93, vcc
	v_add_co_u32_e32 v142, vcc, 0xf000, v92
	s_nop 1
	v_addc_co_u32_e32 v143, vcc, 0, v93, vcc
	global_load_dwordx4 v[184:187], v[92:93], off offset:576
	global_load_dwordx4 v[188:191], v[92:93], off offset:608
	global_load_dwordx4 v[192:195], v[138:139], off offset:576
	global_load_dwordx4 v[196:199], v[138:139], off offset:608
	global_load_dwordx4 v[200:203], v[140:141], off offset:576
	global_load_dwordx4 v[218:221], v[140:141], off offset:608
	global_load_dwordx4 v[222:225], v[142:143], off offset:576
	global_load_dwordx4 v[226:229], v[142:143], off offset:608
	s_waitcnt vmcnt(7) lgkmcnt(1)
	v_mfma_f32_32x32x16_bf16 v[18:33], v[184:187], v[130:133], 0
	s_waitcnt vmcnt(6) lgkmcnt(0)
	v_mfma_f32_32x32x16_bf16 v[18:33], v[188:191], v[134:137], v[18:33]
	s_waitcnt vmcnt(5)
	v_mfma_f32_32x32x16_bf16 v[34:49], v[192:195], v[130:133], 0
	s_waitcnt vmcnt(4)
	v_mfma_f32_32x32x16_bf16 v[34:49], v[196:199], v[134:137], v[34:49]
	s_waitcnt vmcnt(3)
	v_mfma_f32_32x32x16_bf16 v[2:17], v[200:203], v[130:133], 0
	s_waitcnt vmcnt(2)
	v_mfma_f32_32x32x16_bf16 v[2:17], v[218:221], v[134:137], v[2:17]
	s_waitcnt vmcnt(1)
	v_mfma_f32_32x32x16_bf16 v[50:65], v[222:225], v[130:133], 0
	s_waitcnt vmcnt(0)
	v_mfma_f32_32x32x16_bf16 v[50:65], v[226:229], v[134:137], v[50:65]

.LBB0_744:
	v_add_co_u32_e32 v230, vcc, s22, v68
	s_nop 1
	v_addc_co_u32_e32 v231, vcc, -1, v69, vcc
	v_add_co_u32_e32 v232, vcc, s23, v68
	s_nop 1
	v_addc_co_u32_e32 v233, vcc, -1, v69, vcc
	v_add_co_u32_e32 v234, vcc, s24, v68
	s_nop 1
	v_addc_co_u32_e32 v235, vcc, -1, v69, vcc
	v_add_co_u32_e32 v236, vcc, s1, v68
	s_nop 1
	v_addc_co_u32_e32 v237, vcc, -1, v69, vcc
	ds_read_b128 v[130:133], v66
	ds_read_b128 v[134:137], v66 offset:32
	global_load_dwordx4 v[70:73], v[230:231], off
	global_load_dwordx4 v[74:77], v[232:233], off
	global_load_dwordx4 v[78:81], v[234:235], off
	global_load_dwordx4 v[82:85], v[236:237], off
	global_load_dwordx4 v[86:89], v[232:233], off offset:32
	global_load_dwordx4 v[94:97], v[230:231], off offset:32
	global_load_dwordx4 v[98:101], v[234:235], off offset:32
	global_load_dwordx4 v[102:105], v[236:237], off offset:32
	ds_read_b128 v[138:141], v66 offset:64
	ds_read_b128 v[142:145], v66 offset:96
	global_load_dwordx4 v[184:187], v[230:231], off offset:64
	global_load_dwordx4 v[188:191], v[232:233], off offset:64
	global_load_dwordx4 v[192:195], v[234:235], off offset:64
	global_load_dwordx4 v[196:199], v[236:237], off offset:64
	global_load_dwordx4 v[200:203], v[232:233], off offset:96
	global_load_dwordx4 v[218:221], v[230:231], off offset:96
	global_load_dwordx4 v[222:225], v[234:235], off offset:96
	global_load_dwordx4 v[226:229], v[236:237], off offset:96
	s_waitcnt vmcnt(8) lgkmcnt(2)
	v_mfma_f32_32x32x16_bf16 v[34:49], v[70:73], v[130:133], v[34:49]
	v_mfma_f32_32x32x16_bf16 v[50:65], v[74:77], v[130:133], v[50:65]
	v_mfma_f32_32x32x16_bf16 v[18:33], v[78:81], v[130:133], v[18:33]
	v_mfma_f32_32x32x16_bf16 v[2:17], v[82:85], v[130:133], v[2:17]
	v_mfma_f32_32x32x16_bf16 v[50:65], v[86:89], v[134:137], v[50:65]
	v_mfma_f32_32x32x16_bf16 v[34:49], v[94:97], v[134:137], v[34:49]
	v_mfma_f32_32x32x16_bf16 v[18:33], v[98:101], v[134:137], v[18:33]
	v_mfma_f32_32x32x16_bf16 v[2:17], v[102:105], v[134:137], v[2:17]
	ds_read_b128 v[130:133], v66 offset:128
	ds_read_b128 v[134:137], v66 offset:160
	global_load_dwordx4 v[70:73], v[230:231], off offset:128
	global_load_dwordx4 v[74:77], v[232:233], off offset:128
	global_load_dwordx4 v[78:81], v[234:235], off offset:128
	global_load_dwordx4 v[82:85], v[236:237], off offset:128
	global_load_dwordx4 v[86:89], v[232:233], off offset:160
	global_load_dwordx4 v[94:97], v[230:231], off offset:160
	global_load_dwordx4 v[98:101], v[234:235], off offset:160
	global_load_dwordx4 v[102:105], v[236:237], off offset:160
	s_waitcnt vmcnt(8) lgkmcnt(2)
	v_mfma_f32_32x32x16_bf16 v[34:49], v[184:187], v[138:141], v[34:49]
	v_mfma_f32_32x32x16_bf16 v[50:65], v[188:191], v[138:141], v[50:65]
	v_mfma_f32_32x32x16_bf16 v[18:33], v[192:195], v[138:141], v[18:33]
	v_mfma_f32_32x32x16_bf16 v[2:17], v[196:199], v[138:141], v[2:17]
	v_mfma_f32_32x32x16_bf16 v[50:65], v[200:203], v[142:145], v[50:65]
	v_mfma_f32_32x32x16_bf16 v[34:49], v[218:221], v[142:145], v[34:49]
	v_mfma_f32_32x32x16_bf16 v[18:33], v[222:225], v[142:145], v[18:33]
	v_mfma_f32_32x32x16_bf16 v[2:17], v[226:229], v[142:145], v[2:17]
	ds_read_b128 v[138:141], v66 offset:192
	ds_read_b128 v[142:145], v66 offset:224
	global_load_dwordx4 v[184:187], v[230:231], off offset:192
	global_load_dwordx4 v[188:191], v[232:233], off offset:192
	global_load_dwordx4 v[192:195], v[234:235], off offset:192
	global_load_dwordx4 v[196:199], v[236:237], off offset:192
	global_load_dwordx4 v[200:203], v[232:233], off offset:224
	global_load_dwordx4 v[218:221], v[230:231], off offset:224
	global_load_dwordx4 v[222:225], v[234:235], off offset:224
	global_load_dwordx4 v[226:229], v[236:237], off offset:224
	s_waitcnt vmcnt(8) lgkmcnt(2)
	v_mfma_f32_32x32x16_bf16 v[34:49], v[70:73], v[130:133], v[34:49]
	v_mfma_f32_32x32x16_bf16 v[50:65], v[74:77], v[130:133], v[50:65]
	v_mfma_f32_32x32x16_bf16 v[18:33], v[78:81], v[130:133], v[18:33]
	v_mfma_f32_32x32x16_bf16 v[2:17], v[82:85], v[130:133], v[2:17]
	v_mfma_f32_32x32x16_bf16 v[50:65], v[86:89], v[134:137], v[50:65]
	v_mfma_f32_32x32x16_bf16 v[34:49], v[94:97], v[134:137], v[34:49]
	v_mfma_f32_32x32x16_bf16 v[18:33], v[98:101], v[134:137], v[18:33]
	v_mfma_f32_32x32x16_bf16 v[2:17], v[102:105], v[134:137], v[2:17]
	ds_read_b128 v[130:133], v66 offset:256
	ds_read_b128 v[134:137], v66 offset:288
	global_load_dwordx4 v[70:73], v[230:231], off offset:256
	global_load_dwordx4 v[74:77], v[232:233], off offset:256
	global_load_dwordx4 v[78:81], v[234:235], off offset:256
	global_load_dwordx4 v[82:85], v[236:237], off offset:256
	global_load_dwordx4 v[86:89], v[232:233], off offset:288
	global_load_dwordx4 v[94:97], v[230:231], off offset:288
	global_load_dwordx4 v[98:101], v[234:235], off offset:288
	global_load_dwordx4 v[102:105], v[236:237], off offset:288
	s_waitcnt vmcnt(8) lgkmcnt(2)
	v_mfma_f32_32x32x16_bf16 v[34:49], v[184:187], v[138:141], v[34:49]
	v_mfma_f32_32x32x16_bf16 v[50:65], v[188:191], v[138:141], v[50:65]
	v_mfma_f32_32x32x16_bf16 v[18:33], v[192:195], v[138:141], v[18:33]
	v_mfma_f32_32x32x16_bf16 v[2:17], v[196:199], v[138:141], v[2:17]
	v_mfma_f32_32x32x16_bf16 v[50:65], v[200:203], v[142:145], v[50:65]
	v_mfma_f32_32x32x16_bf16 v[34:49], v[218:221], v[142:145], v[34:49]
	v_mfma_f32_32x32x16_bf16 v[18:33], v[222:225], v[142:145], v[18:33]
	v_mfma_f32_32x32x16_bf16 v[2:17], v[226:229], v[142:145], v[2:17]
	s_waitcnt vmcnt(0) lgkmcnt(0)
	v_mfma_f32_32x32x16_bf16 v[34:49], v[70:73], v[130:133], v[34:49]
	v_mfma_f32_32x32x16_bf16 v[50:65], v[74:77], v[130:133], v[50:65]
	v_mfma_f32_32x32x16_bf16 v[18:33], v[78:81], v[130:133], v[18:33]
	v_mfma_f32_32x32x16_bf16 v[2:17], v[82:85], v[130:133], v[2:17]
	v_mfma_f32_32x32x16_bf16 v[50:65], v[86:89], v[134:137], v[50:65]
	v_mfma_f32_32x32x16_bf16 v[34:49], v[94:97], v[134:137], v[34:49]
	v_mfma_f32_32x32x16_bf16 v[18:33], v[98:101], v[134:137], v[18:33]
	v_mfma_f32_32x32x16_bf16 v[2:17], v[102:105], v[134:137], v[2:17]
	s_nop 0
	v_mov_b32_e32 v66, v151
	v_mov_b32_e32 v68, v128
	v_mov_b32_e32 v69, v152
	s_nop 3
	ds_write_b128 v159, v[34:37] offset:21504
	ds_write_b128 v159, v[38:41] offset:21536
	ds_write_b128 v159, v[42:45] offset:21568
	ds_write_b128 v159, v[46:49] offset:21600
	ds_write_b128 v159, v[50:53] offset:21632
	ds_write_b128 v159, v[54:57] offset:21664
	ds_write_b128 v159, v[58:61] offset:21696
	ds_write_b128 v159, v[62:65] offset:21728
	v_lshl_add_u64 v[34:35], v[66:67], 1, s[12:13]
	s_mov_b32 s0, s57
	v_mov_b32_e32 v36, v157
	s_mov_b32 s22, s58

.LBB0_748:
	ds_read_b128 v[6:9], v4
	s_ashr_i32 s1, s0, 31
	s_lshl_b64 s[44:45], s[0:1], 11
	v_lshl_add_u64 v[10:11], v[2:3], 0, s[44:45]
	s_add_i32 s44, s0, 4
	s_waitcnt lgkmcnt(0)
	v_bfe_u32 v5, v6, 16, 1
	v_add3_u32 v5, v6, v5, s33
	v_bfe_u32 v6, v7, 16, 1
	v_lshrrev_b32_e32 v5, 16, v5
	v_add3_u32 v6, v7, v6, s33
	v_and_or_b32 v6, v6, s30, v5
	v_bfe_u32 v5, v8, 16, 1
	v_add3_u32 v5, v8, v5, s33
	v_bfe_u32 v7, v9, 16, 1
	v_lshrrev_b32_e32 v5, 16, v5
	v_add3_u32 v7, v9, v7, s33
	v_and_or_b32 v7, v7, s30, v5
	global_store_dwordx2 v[10:11], v[6:7], off
	ds_read_b128 v[6:9], v4 offset:1088
	s_ashr_i32 s45, s44, 31
	s_lshl_b64 s[44:45], s[44:45], 11
	v_lshl_add_u64 v[10:11], v[2:3], 0, s[44:45]
	s_add_i32 s44, s0, 8
	s_waitcnt lgkmcnt(0)
	v_bfe_u32 v5, v6, 16, 1
	v_add3_u32 v5, v6, v5, s33
	v_bfe_u32 v6, v7, 16, 1
	v_lshrrev_b32_e32 v5, 16, v5
	v_add3_u32 v6, v7, v6, s33
	v_and_or_b32 v6, v6, s30, v5
	v_bfe_u32 v5, v8, 16, 1
	v_add3_u32 v5, v8, v5, s33
	v_bfe_u32 v7, v9, 16, 1
	v_lshrrev_b32_e32 v5, 16, v5
	v_add3_u32 v7, v9, v7, s33
	v_and_or_b32 v7, v7, s30, v5
	global_store_dwordx2 v[10:11], v[6:7], off
	ds_read_b128 v[6:9], v4 offset:2176
	s_ashr_i32 s45, s44, 31
	s_lshl_b64 s[44:45], s[44:45], 11
	v_lshl_add_u64 v[10:11], v[2:3], 0, s[44:45]
	s_add_i32 s44, s0, 12
	s_waitcnt lgkmcnt(0)
	v_bfe_u32 v5, v6, 16, 1
	v_add3_u32 v5, v6, v5, s33
	v_bfe_u32 v6, v7, 16, 1
	v_lshrrev_b32_e32 v5, 16, v5
	v_add3_u32 v6, v7, v6, s33
	v_and_or_b32 v6, v6, s30, v5
	v_bfe_u32 v5, v8, 16, 1
	v_add3_u32 v5, v8, v5, s33
	v_bfe_u32 v7, v9, 16, 1
	v_lshrrev_b32_e32 v5, 16, v5
	v_add3_u32 v7, v9, v7, s33
	v_and_or_b32 v7, v7, s30, v5
	global_store_dwordx2 v[10:11], v[6:7], off
	ds_read_b128 v[6:9], v4 offset:3264
	s_ashr_i32 s45, s44, 31
	s_lshl_b64 s[44:45], s[44:45], 11
	s_add_i32 s22, s22, -1
	s_add_i32 s0, s0, 16
	s_waitcnt lgkmcnt(0)
	v_bfe_u32 v5, v6, 16, 1
	v_add3_u32 v5, v6, v5, s33
	v_bfe_u32 v6, v7, 16, 1
	v_lshrrev_b32_e32 v5, 16, v5
	v_add3_u32 v6, v7, v6, s33
	v_and_or_b32 v6, v6, s30, v5
	v_bfe_u32 v5, v8, 16, 1
	v_add3_u32 v5, v8, v5, s33
	v_bfe_u32 v7, v9, 16, 1
	v_lshrrev_b32_e32 v5, 16, v5
	v_add3_u32 v7, v9, v7, s33
	v_lshl_add_u64 v[10:11], v[2:3], 0, s[44:45]
	v_and_or_b32 v7, v7, s30, v5
	v_add_u32_e32 v4, 0x1100, v4
	s_cmp_lg_u32 s22, 0
	global_store_dwordx2 v[10:11], v[6:7], off
	s_cbranch_scc1 .LBB0_748
	ds_read_b128 v[50:53], v150 offset:128
	ds_read_b128 v[54:57], v150 offset:160
	ds_read_b128 v[58:61], v150 offset:192
	ds_read_b128 v[62:65], v150 offset:224
	v_add_co_u32_e32 v144, vcc, 0x5000, v92
	s_nop 1
	v_addc_co_u32_e32 v145, vcc, 0, v93, vcc
	v_add_co_u32_e32 v146, vcc, 0xa000, v92
	s_nop 1
	v_addc_co_u32_e32 v147, vcc, 0, v93, vcc
	v_add_co_u32_e32 v166, vcc, 0xf000, v92
	s_nop 1
	v_addc_co_u32_e32 v167, vcc, 0, v93, vcc
	v_mov_b32_e32 v66, v152
	v_mov_b32_e32 v84, v151
	v_mov_b32_e32 v134, v128
	v_mov_b32_e32 v135, v67
	v_readlane_b32 s0, v252, 21
	v_readlane_b32 s1, v252, 22
	s_mov_b32 s25, 0
	v_add_u32_e32 v161, s57, v149
	s_movk_i32 s28, 0x2000
	global_load_dwordx4 v[184:187], v[92:93], off offset:128
	global_load_dwordx4 v[188:191], v[92:93], off offset:160
	global_load_dwordx4 v[192:195], v[144:145], off offset:128
	global_load_dwordx4 v[196:199], v[144:145], off offset:160
	global_load_dwordx4 v[200:203], v[146:147], off offset:128
	global_load_dwordx4 v[218:221], v[146:147], off offset:160
	global_load_dwordx4 v[222:225], v[92:93], off offset:192
	global_load_dwordx4 v[226:229], v[144:145], off offset:192
	global_load_dwordx4 v[230:233], v[146:147], off offset:192
	global_load_dwordx4 v[234:237], v[92:93], off offset:224
	global_load_dwordx4 v[238:241], v[146:147], off offset:224
	global_load_dwordx4 v[140:143], v[144:145], off offset:224
	global_load_dwordx4 v[68:71], v[166:167], off offset:128
	global_load_dwordx4 v[72:75], v[166:167], off offset:160
	global_load_dwordx4 v[76:79], v[166:167], off offset:192
	global_load_dwordx4 v[80:83], v[166:167], off offset:224
	global_load_dwordx4 v[84:87], v[114:115], off
	global_load_dwordx4 v[88:91], v[116:117], off
	global_load_dwordx4 v[92:95], v[120:121], off
	global_load_dwordx4 v[96:99], v[108:109], off
	global_load_dwordx4 v[100:103], v[126:127], off
	global_load_dwordx4 v[104:107], v[122:123], off
	v_lshlrev_b64 v[138:139], 1, v[134:135]
	v_lshl_add_u64 v[134:135], s[0:1], 0, v[138:139]
	v_readlane_b32 s0, v252, 23
	v_readlane_b32 s1, v252, 24
	v_lshl_add_u64 v[136:137], s[0:1], 0, v[138:139]
	s_waitcnt vmcnt(21) lgkmcnt(3)
	v_mfma_f32_32x32x16_bf16 v[18:33], v[184:187], v[50:53], 0
	s_waitcnt vmcnt(20) lgkmcnt(2)
	v_mfma_f32_32x32x16_bf16 v[18:33], v[188:191], v[54:57], v[18:33]
	s_waitcnt vmcnt(19) lgkmcnt(3)
	v_mfma_f32_32x32x16_bf16 v[34:49], v[192:195], v[50:53], 0
	s_waitcnt vmcnt(18) lgkmcnt(2)
	v_mfma_f32_32x32x16_bf16 v[34:49], v[196:199], v[54:57], v[34:49]
	s_waitcnt vmcnt(17) lgkmcnt(3)
	v_mfma_f32_32x32x16_bf16 v[2:17], v[200:203], v[50:53], 0
	s_waitcnt vmcnt(16) lgkmcnt(2)
	v_mfma_f32_32x32x16_bf16 v[2:17], v[218:221], v[54:57], v[2:17]
	s_waitcnt vmcnt(15) lgkmcnt(1)
	v_mfma_f32_32x32x16_bf16 v[18:33], v[222:225], v[58:61], v[18:33]
	s_waitcnt vmcnt(14) lgkmcnt(1)
	v_mfma_f32_32x32x16_bf16 v[34:49], v[226:229], v[58:61], v[34:49]
	s_waitcnt vmcnt(13) lgkmcnt(1)
	v_mfma_f32_32x32x16_bf16 v[2:17], v[230:233], v[58:61], v[2:17]
	s_waitcnt vmcnt(12) lgkmcnt(0)
	v_mfma_f32_32x32x16_bf16 v[18:33], v[234:237], v[62:65], v[18:33]
	s_waitcnt vmcnt(11) lgkmcnt(0)
	v_mfma_f32_32x32x16_bf16 v[2:17], v[238:241], v[62:65], v[2:17]
	s_waitcnt vmcnt(10) lgkmcnt(0)
	v_mfma_f32_32x32x16_bf16 v[34:49], v[140:143], v[62:65], v[34:49]
	v_lshl_add_u64 v[130:131], v[66:67], 1, s[14:15]
	v_lshl_add_u64 v[132:133], s[94:95], 0, v[138:139]
	v_lshl_add_u64 v[138:139], s[82:83], 0, v[138:139]
	v_mov_b32_e32 v66, v157
	s_nop 5
	ds_write_b128 v159, v[18:21] offset:21504
	ds_write_b128 v159, v[22:25] offset:21536
	ds_write_b128 v159, v[26:29] offset:21568
	ds_write_b128 v159, v[30:33] offset:21600
	ds_write_b128 v159, v[34:37] offset:21632
	ds_write_b128 v159, v[38:41] offset:21664
	ds_write_b128 v159, v[42:45] offset:21696
	ds_write_b128 v159, v[46:49] offset:21728
	s_branch .LBB0_751
